# attention unit: pass-1 key tile 0, pass-2 value tile 0 and the three gate values all loaded with the Q loads at the unit top; on top of v94
# speedup vs baseline: 1.0021x; 1.0021x over previous
.LBB0_1183:
	s_bfe_u32 s0, s41, 0x50003
	s_ashr_i32 s86, s41, 3
	s_and_b32 s36, s86, 0xffffffe0
	s_and_b32 s1, s41, 0x100
	s_xor_b32 s12, s0, 31
	s_cmp_eq_u32 s1, 0
	s_cselect_b32 s67, s0, s12
	s_lshl_b32 s0, s41, 2
	s_and_b32 s0, s0, 12
	s_or_b32 s33, s67, s36
	s_or_b32 s17, s0, s66
	s_lshl_b32 s0, s41, 11
	v_lshl_add_u32 v1, s33, 6, v158
	s_and_b32 s0, s0, 0x2000
	v_add_u32_e32 v36, s0, v1
	v_ashrrev_i32_e32 v37, 31, v36
	v_lshlrev_b64 v[2:3], 11, v[36:37]
	v_lshl_add_u64 v[2:3], s[18:19], 0, v[2:3]
	s_lshl_b32 s48, s17, 7
	v_lshl_add_u64 v[2:3], v[2:3], 0, s[48:49]
	v_lshl_add_u64 v[2:3], v[2:3], 0, v[176:177]
	global_load_dwordx4 v[100:103], v[2:3], off
	global_load_dwordx4 v[104:107], v[2:3], off offset:32
	global_load_dwordx4 v[108:111], v[2:3], off offset:64
	global_load_dwordx4 v[112:115], v[2:3], off offset:96
	s_and_b32 s100, s41, 7
	s_lshl_b32 s100, s100, 16
	v_readlane_b32 s98, v255, 10
	v_readlane_b32 s99, v255, 11
	s_nop 1
	s_add_u32 s98, s98, s100
	s_addc_u32 s99, s99, 0
	v_lshl_add_u64 v[242:243], v[120:121], 1, s[98:99]
	global_load_dwordx4 v[238:241], v[242:243], off
	v_readlane_b32 s98, v255, 12
	v_readlane_b32 s99, v255, 14
	v_lshlrev_b32_e32 v242, 1, v122
	v_mov_b32_e32 v243, v177
	s_add_u32 s98, s98, s100
	s_addc_u32 s99, s99, 0
	v_lshl_add_u64 v[242:243], s[98:99], 0, v[242:243]
	v_lshl_add_u64 v[242:243], v[124:125], 1, v[242:243]
	global_load_dwordx4 v[242:245], v[242:243], off
	v_mov_b64_e32 v[246:247], s[20:21]
	s_movk_i32 s100, 0xc0
	v_mad_i64_i32 v[246:247], s[98:99], v36, s100, v[246:247]
	s_lshl_b32 s100, s17, 2
	s_mov_b32 s101, 0
	v_lshl_add_u64 v[246:247], v[246:247], 0, s[100:101]
	global_load_dword v223, v[246:247], off
	global_load_dword v249, v[246:247], off offset:64
	global_load_dword v251, v[246:247], off offset:128
	s_waitcnt vmcnt(8)
	v_and_b32_e32 v0, 0xffff0000, v100
	v_lshlrev_b32_e32 v2, 16, v100
	v_mul_f32_e32 v0, v0, v0
	v_fmac_f32_e32 v0, v2, v2
	v_lshlrev_b32_e32 v2, 16, v101
	v_fmac_f32_e32 v0, v2, v2
	v_and_b32_e32 v2, 0xffff0000, v101
	v_fmac_f32_e32 v0, v2, v2
	v_lshlrev_b32_e32 v2, 16, v102
	v_fmac_f32_e32 v0, v2, v2
	v_and_b32_e32 v2, 0xffff0000, v102
	v_fmac_f32_e32 v0, v2, v2
	v_lshlrev_b32_e32 v2, 16, v103
	v_fmac_f32_e32 v0, v2, v2
	v_and_b32_e32 v2, 0xffff0000, v103
	v_fmac_f32_e32 v0, v2, v2
	s_waitcnt vmcnt(7)
	v_lshlrev_b32_e32 v2, 16, v104
	v_fmac_f32_e32 v0, v2, v2
	v_and_b32_e32 v2, 0xffff0000, v104
	v_fmac_f32_e32 v0, v2, v2
	v_lshlrev_b32_e32 v2, 16, v105
	v_fmac_f32_e32 v0, v2, v2
	v_and_b32_e32 v2, 0xffff0000, v105
	v_fmac_f32_e32 v0, v2, v2
	v_lshlrev_b32_e32 v2, 16, v106
	v_fmac_f32_e32 v0, v2, v2
	v_and_b32_e32 v2, 0xffff0000, v106
	v_fmac_f32_e32 v0, v2, v2
	v_lshlrev_b32_e32 v2, 16, v107
	v_fmac_f32_e32 v0, v2, v2
	v_and_b32_e32 v2, 0xffff0000, v107
	v_fmac_f32_e32 v0, v2, v2
	s_waitcnt vmcnt(6)
	v_lshlrev_b32_e32 v2, 16, v108
	v_fmac_f32_e32 v0, v2, v2
	v_and_b32_e32 v2, 0xffff0000, v108
	v_fmac_f32_e32 v0, v2, v2
	v_lshlrev_b32_e32 v2, 16, v109
	v_fmac_f32_e32 v0, v2, v2
	v_and_b32_e32 v2, 0xffff0000, v109
	v_fmac_f32_e32 v0, v2, v2
	v_lshlrev_b32_e32 v2, 16, v110
	v_fmac_f32_e32 v0, v2, v2
	v_and_b32_e32 v2, 0xffff0000, v110
	v_fmac_f32_e32 v0, v2, v2
	v_lshlrev_b32_e32 v2, 16, v111
	v_fmac_f32_e32 v0, v2, v2
	v_and_b32_e32 v2, 0xffff0000, v111
	v_fmac_f32_e32 v0, v2, v2
	s_waitcnt vmcnt(5)
	v_lshlrev_b32_e32 v2, 16, v112
	v_fmac_f32_e32 v0, v2, v2
	v_and_b32_e32 v2, 0xffff0000, v112
	v_fmac_f32_e32 v0, v2, v2
	v_lshlrev_b32_e32 v2, 16, v113
	v_fmac_f32_e32 v0, v2, v2
	v_and_b32_e32 v2, 0xffff0000, v113
	v_fmac_f32_e32 v0, v2, v2
	v_lshlrev_b32_e32 v2, 16, v114
	v_fmac_f32_e32 v0, v2, v2
	v_and_b32_e32 v2, 0xffff0000, v114
	v_fmac_f32_e32 v0, v2, v2
	v_lshlrev_b32_e32 v2, 16, v115
	v_fmac_f32_e32 v0, v2, v2
	v_and_b32_e32 v2, 0xffff0000, v115
	v_fmac_f32_e32 v0, v2, v2
	v_mov_b32_e32 v2, v0
	s_nop 1
	v_permlane32_swap_b32_e32 v0, v2
	s_mov_b64 s[0:1], exec
	v_readlane_b32 s12, v255, 16
	v_readlane_b32 s13, v255, 17
	s_and_b64 s[12:13], s[0:1], s[12:13]
	s_mov_b64 exec, s[12:13]
	s_cbranch_execz .LBB0_1186
	s_mov_b64 s[12:13], 0
	v_mov_b32_e32 v3, v201
	v_mov_b32_e32 v4, v200

.LBB0_1201:
	s_andn2_b64 vcc, exec, s[14:15]
	s_waitcnt vmcnt(0)
	v_mov_b32_e32 v74, v223
	ds_write_b128 v163, v[238:241]
	ds_write_b16 v167, v242 offset:9216
	ds_write_b16_d16_hi v167, v242 offset:9352
	ds_write_b16 v167, v243 offset:9488
	ds_write_b16_d16_hi v167, v243 offset:9624
	ds_write_b16 v167, v244 offset:9760
	ds_write_b16_d16_hi v167, v244 offset:9896
	ds_write_b16 v167, v245 offset:10032
	ds_write_b16_d16_hi v167, v245 offset:10168
	s_cbranch_vccnz .LBB0_1203
	v_mov_b32_e32 v73, v177
	v_lshl_add_u64 v[2:3], s[0:1], 0, v[72:73]
	v_add_co_u32_e32 v4, vcc, 0x2000, v38
	v_lshl_add_u64 v[2:3], v[124:125], 1, v[2:3]
	s_nop 0
	v_addc_co_u32_e32 v5, vcc, 0, v39, vcc
	v_add_co_u32_e32 v2, vcc, 0x2000, v2
	s_nop 1
	v_addc_co_u32_e32 v3, vcc, 0, v3, vcc
	global_load_dwordx4 v[64:67], v[4:5], off
	global_load_dwordx4 v[96:99], v[2:3], off

.LBB0_1298:
	v_mov_b32_e32 v32, v73
	s_nop 1
	v_permlane32_swap_b32_e32 v73, v32
	v_add_f32_e32 v32, v73, v32
	v_div_scale_f32 v34, s[16:17], v32, v32, 1.0
	v_rcp_f32_e32 v35, v34
	v_cmp_lt_f32_e64 s[14:15], 0, v32
	s_lshl_b32 s0, s88, 19
	v_readlane_b32 s2, v255, 7
	v_fma_f32 v36, -v34, v35, 1.0
	v_fmac_f32_e32 v35, v36, v35
	v_div_scale_f32 v36, vcc, 1.0, v32, 1.0
	v_mul_f32_e32 v37, v36, v35
	v_fma_f32 v38, -v34, v37, v36
	v_fmac_f32_e32 v37, v38, v35
	v_fma_f32 v34, -v34, v37, v36
	v_div_fmas_f32 v34, v34, v35, v37
	v_div_fixup_f32 v32, v34, v32, 1.0
	ds_read2st64_b32 v[34:35], v157 offset0:128 offset1:136
	v_cndmask_b32_e64 v32, 0, v32, s[14:15]
	s_lshl_b32 s14, s0, 1
	s_add_u32 s0, s30, s14
	s_addc_u32 s1, s3, 0
	s_add_u32 s16, s2, s14
	v_readlane_b32 s2, v255, 9
	s_addc_u32 s17, s2, 0
	s_add_i32 s14, s33, -8
	s_cmp_gt_i32 s33, 7
	s_cselect_b32 s14, s14, 0
	s_ashr_i32 s15, s14, 31
	s_lshl_b64 s[34:35], s[14:15], 13
	s_add_u32 s34, s0, s34
	s_addc_u32 s35, s1, s35
	s_and_b64 vcc, exec, s[12:13]
	s_waitcnt vmcnt(0)
	v_mov_b32_e32 v33, v249
	v_mul_f32_e32 v36, v33, v32
	s_waitcnt lgkmcnt(0)
	v_fma_f32 v0, v0, v36, v34
	v_fmac_f32_e32 v35, v1, v36
	ds_write2st64_b32 v157, v0, v35 offset0:128 offset1:136
	ds_read2st64_b32 v[0:1], v157 offset0:16 offset1:24
	ds_read2st64_b32 v[32:33], v157 offset1:8
	s_waitcnt lgkmcnt(1)
	v_fma_f32 v0, v18, v36, v0
	v_fmac_f32_e32 v1, v19, v36
	ds_write2st64_b32 v157, v0, v1 offset0:16 offset1:24
	ds_read2st64_b32 v[0:1], v157 offset0:32 offset1:40
	s_waitcnt lgkmcnt(2)
	v_fma_f32 v16, v16, v36, v32
	v_fmac_f32_e32 v33, v17, v36
	ds_write2st64_b32 v157, v16, v33 offset1:8
	ds_read2st64_b32 v[16:17], v157 offset0:144 offset1:152
	s_waitcnt lgkmcnt(2)
	v_fma_f32 v0, v20, v36, v0
	v_fmac_f32_e32 v1, v21, v36
	ds_write2st64_b32 v157, v0, v1 offset0:32 offset1:40
	ds_read2st64_b32 v[0:1], v157 offset0:48 offset1:56
	s_waitcnt lgkmcnt(2)
	v_fma_f32 v2, v2, v36, v16
	v_fmac_f32_e32 v17, v3, v36
	ds_write2st64_b32 v157, v2, v17 offset0:144 offset1:152
	ds_read2st64_b32 v[2:3], v157 offset0:160 offset1:168
	s_waitcnt lgkmcnt(2)
	v_fma_f32 v0, v22, v36, v0
	v_fmac_f32_e32 v1, v23, v36
	ds_write2st64_b32 v157, v0, v1 offset0:48 offset1:56
	ds_read2st64_b32 v[0:1], v157 offset0:64 offset1:72
	s_waitcnt lgkmcnt(2)
	v_fma_f32 v2, v4, v36, v2
	v_fmac_f32_e32 v3, v5, v36
	ds_write2st64_b32 v157, v2, v3 offset0:160 offset1:168
	ds_read2st64_b32 v[2:3], v157 offset0:176 offset1:184
	s_waitcnt lgkmcnt(2)
	v_fma_f32 v0, v24, v36, v0
	v_fmac_f32_e32 v1, v25, v36
	ds_write2st64_b32 v157, v0, v1 offset0:64 offset1:72
	ds_read2st64_b32 v[0:1], v157 offset0:80 offset1:88
	s_waitcnt lgkmcnt(2)
	v_fma_f32 v2, v6, v36, v2
	v_fmac_f32_e32 v3, v7, v36
	ds_write2st64_b32 v157, v2, v3 offset0:176 offset1:184
	ds_read2st64_b32 v[2:3], v157 offset0:192 offset1:200
	s_waitcnt lgkmcnt(2)
	v_fma_f32 v0, v26, v36, v0
	v_fmac_f32_e32 v1, v27, v36
	ds_write2st64_b32 v157, v0, v1 offset0:80 offset1:88
	ds_read2st64_b32 v[0:1], v157 offset0:96 offset1:104
	s_waitcnt lgkmcnt(2)
	v_fma_f32 v2, v8, v36, v2
	v_fmac_f32_e32 v3, v9, v36
	ds_write2st64_b32 v157, v2, v3 offset0:192 offset1:200
	ds_read2st64_b32 v[2:3], v157 offset0:208 offset1:216
	s_waitcnt lgkmcnt(2)
	v_fma_f32 v0, v28, v36, v0
	v_fmac_f32_e32 v1, v29, v36
	ds_write2st64_b32 v157, v0, v1 offset0:96 offset1:104
	ds_read2st64_b32 v[0:1], v157 offset0:112 offset1:120
	s_waitcnt lgkmcnt(2)
	v_fma_f32 v2, v10, v36, v2
	v_fmac_f32_e32 v3, v11, v36
	ds_write2st64_b32 v157, v2, v3 offset0:208 offset1:216
	ds_read2st64_b32 v[2:3], v157 offset0:224 offset1:232
	s_waitcnt lgkmcnt(2)
	v_fma_f32 v0, v30, v36, v0
	v_fmac_f32_e32 v1, v31, v36
	ds_write2st64_b32 v157, v0, v1 offset0:112 offset1:120
	v_lshl_add_u64 v[0:1], v[120:121], 1, s[34:35]
	global_load_dwordx4 v[116:119], v[0:1], off
	s_waitcnt lgkmcnt(1)
	v_fma_f32 v2, v12, v36, v2
	v_fmac_f32_e32 v3, v13, v36
	ds_write2st64_b32 v157, v2, v3 offset0:224 offset1:232
	ds_read2st64_b32 v[2:3], v157 offset0:240 offset1:248
	s_waitcnt lgkmcnt(0)
	v_fma_f32 v2, v14, v36, v2
	v_fmac_f32_e32 v3, v15, v36
	ds_write2st64_b32 v157, v2, v3 offset0:240 offset1:248
	s_cbranch_vccnz .LBB0_1300
	s_lshl_b64 s[34:35], s[14:15], 12
	s_lshl_b64 s[34:35], s[34:35], 1
	s_add_u32 s34, s16, s34
	s_addc_u32 s35, s17, s35
	v_mov_b32_e32 v73, v177
	v_lshl_add_u64 v[0:1], s[34:35], 0, v[72:73]
	v_lshl_add_u64 v[0:1], v[124:125], 1, v[0:1]
	global_load_dwordx4 v[96:99], v[0:1], off
